# attention combine loop software-pipelined (8 row pairs per trip, loads issued up front, DPP row reductions) on top of the rewritten O epilogue
# speedup vs baseline: 1.0073x; 1.0019x over previous
; __device__ __forceinline__ void attention_phase(char* lds, const bf16_t* Q, const bf16_t* K, const bf16_t* V, bf16_t* O1, bf16_t* O2, bf16_t* OC, const float* lamv, const float* subln, int G, int bid) {
;     ...
;         for (int i = 0; i < 32; ++i) {
;             const int rr = wave * 64 + i * 2 + (lane >> 5), qb = (rr < 256) ? x : 7 - x;
;             const size_t ro = ((size_t)b * SEQ + qb * 256 + (rr & 255)) * DM + h * 256 + (lane & 31) * 8;
;             float a[8], c[8], d[8]; float ss = 0.f;
;             unpack8(*(const u32x4*)(O1 + ro), a); unpack8(*(const u32x4*)(O2 + ro), c);
; #pragma unroll
;             for (int e = 0; e < 8; ++e) { d[e] = a[e] - lam * c[e]; ss += d[e] * d[e]; }
.Lcmb_loop:
	v_add_u32_e32 v24, s2, v15
	v_cmp_gt_i32_e32 vcc, s36, v24
	v_mov_b32_e32 v25, s49
	v_mov_b32_e32 v26, s17
	v_cndmask_b32_e32 v25, v25, v26, vcc
	v_and_b32_e32 v24, 0xff, v24
	v_or3_b32 v24, s18, v25, v24
	v_mov_b32_e32 v25, s19
	v_lshlrev_b64 v[32:33], 12, v[24:25]
	v_lshl_or_b32 v32, v8, 1, v32
	v_lshl_add_u64 v[26:27], s[8:9], 0, v[32:33]
	v_lshl_add_u64 v[28:29], s[12:13], 0, v[32:33]
	global_load_dwordx4 v[84:87], v[26:27], off
	global_load_dwordx4 v[132:135], v[28:29], off
	v_add_u32_e32 v24, s2, v15
	v_add_u32_e32 v24, 2, v24
	v_cmp_gt_i32_e32 vcc, s36, v24
	v_mov_b32_e32 v25, s49
	v_mov_b32_e32 v26, s17
	v_cndmask_b32_e32 v25, v25, v26, vcc
	v_and_b32_e32 v24, 0xff, v24
	v_or3_b32 v24, s18, v25, v24
	v_mov_b32_e32 v25, s19
	v_lshlrev_b64 v[34:35], 12, v[24:25]
	v_lshl_or_b32 v34, v8, 1, v34
	v_lshl_add_u64 v[26:27], s[8:9], 0, v[34:35]
	v_lshl_add_u64 v[28:29], s[12:13], 0, v[34:35]
	global_load_dwordx4 v[88:91], v[26:27], off
	global_load_dwordx4 v[136:139], v[28:29], off
	v_add_u32_e32 v24, s2, v15
	v_add_u32_e32 v24, 4, v24
	v_cmp_gt_i32_e32 vcc, s36, v24
	v_mov_b32_e32 v25, s49
	v_mov_b32_e32 v26, s17
	v_cndmask_b32_e32 v25, v25, v26, vcc
	v_and_b32_e32 v24, 0xff, v24
	v_or3_b32 v24, s18, v25, v24
	v_mov_b32_e32 v25, s19
	v_lshlrev_b64 v[36:37], 12, v[24:25]
	v_lshl_or_b32 v36, v8, 1, v36
	v_lshl_add_u64 v[26:27], s[8:9], 0, v[36:37]
	v_lshl_add_u64 v[28:29], s[12:13], 0, v[36:37]
	global_load_dwordx4 v[92:95], v[26:27], off
	global_load_dwordx4 v[140:143], v[28:29], off
	v_add_u32_e32 v24, s2, v15
	v_add_u32_e32 v24, 6, v24
	v_cmp_gt_i32_e32 vcc, s36, v24
	v_mov_b32_e32 v25, s49
	v_mov_b32_e32 v26, s17
	v_cndmask_b32_e32 v25, v25, v26, vcc
	v_and_b32_e32 v24, 0xff, v24
	v_or3_b32 v24, s18, v25, v24
	v_mov_b32_e32 v25, s19
	v_lshlrev_b64 v[38:39], 12, v[24:25]
	v_lshl_or_b32 v38, v8, 1, v38
	v_lshl_add_u64 v[26:27], s[8:9], 0, v[38:39]
	v_lshl_add_u64 v[28:29], s[12:13], 0, v[38:39]
	global_load_dwordx4 v[96:99], v[26:27], off
	global_load_dwordx4 v[144:147], v[28:29], off
	v_add_u32_e32 v24, s2, v15
	v_add_u32_e32 v24, 8, v24
	v_cmp_gt_i32_e32 vcc, s36, v24
	v_mov_b32_e32 v25, s49
	v_mov_b32_e32 v26, s17
	v_cndmask_b32_e32 v25, v25, v26, vcc
	v_and_b32_e32 v24, 0xff, v24
	v_or3_b32 v24, s18, v25, v24
	v_mov_b32_e32 v25, s19
	v_lshlrev_b64 v[40:41], 12, v[24:25]
	v_lshl_or_b32 v40, v8, 1, v40
	v_lshl_add_u64 v[26:27], s[8:9], 0, v[40:41]
	v_lshl_add_u64 v[28:29], s[12:13], 0, v[40:41]
	global_load_dwordx4 v[100:103], v[26:27], off
	global_load_dwordx4 v[148:151], v[28:29], off
	v_add_u32_e32 v24, s2, v15
	v_add_u32_e32 v24, 10, v24
	v_cmp_gt_i32_e32 vcc, s36, v24
	v_mov_b32_e32 v25, s49
	v_mov_b32_e32 v26, s17
	v_cndmask_b32_e32 v25, v25, v26, vcc
	v_and_b32_e32 v24, 0xff, v24
	v_or3_b32 v24, s18, v25, v24
	v_mov_b32_e32 v25, s19
	v_lshlrev_b64 v[42:43], 12, v[24:25]
	v_lshl_or_b32 v42, v8, 1, v42
	v_lshl_add_u64 v[26:27], s[8:9], 0, v[42:43]
	v_lshl_add_u64 v[28:29], s[12:13], 0, v[42:43]
	global_load_dwordx4 v[104:107], v[26:27], off
	global_load_dwordx4 v[152:155], v[28:29], off
	v_add_u32_e32 v24, s2, v15
	v_add_u32_e32 v24, 12, v24
	v_cmp_gt_i32_e32 vcc, s36, v24
	v_mov_b32_e32 v25, s49
	v_mov_b32_e32 v26, s17
	v_cndmask_b32_e32 v25, v25, v26, vcc
	v_and_b32_e32 v24, 0xff, v24
	v_or3_b32 v24, s18, v25, v24
	v_mov_b32_e32 v25, s19
	v_lshlrev_b64 v[44:45], 12, v[24:25]
	v_lshl_or_b32 v44, v8, 1, v44
	v_lshl_add_u64 v[26:27], s[8:9], 0, v[44:45]
	v_lshl_add_u64 v[28:29], s[12:13], 0, v[44:45]
	global_load_dwordx4 v[108:111], v[26:27], off
	global_load_dwordx4 v[156:159], v[28:29], off
	v_add_u32_e32 v24, s2, v15
	v_add_u32_e32 v24, 14, v24
	v_cmp_gt_i32_e32 vcc, s36, v24
	v_mov_b32_e32 v25, s49
	v_mov_b32_e32 v26, s17
	v_cndmask_b32_e32 v25, v25, v26, vcc
	v_and_b32_e32 v24, 0xff, v24
	v_or3_b32 v24, s18, v25, v24
	v_mov_b32_e32 v25, s19
	v_lshlrev_b64 v[46:47], 12, v[24:25]
	v_lshl_or_b32 v46, v8, 1, v46
	v_lshl_add_u64 v[26:27], s[8:9], 0, v[46:47]
	v_lshl_add_u64 v[28:29], s[12:13], 0, v[46:47]
	global_load_dwordx4 v[112:115], v[26:27], off
	global_load_dwordx4 v[160:163], v[28:29], off
	s_waitcnt vmcnt(14)
	v_lshlrev_b32_e32 v24, 16, v84
	v_and_b32_e32 v84, 0xffff0000, v84
	v_lshlrev_b32_e32 v25, 16, v132
	v_and_b32_e32 v132, 0xffff0000, v132
	v_fma_f32 v132, -v10, v132, v84
	v_fma_f32 v84, -v10, v25, v24
	v_lshlrev_b32_e32 v24, 16, v85
	v_and_b32_e32 v85, 0xffff0000, v85
	v_lshlrev_b32_e32 v25, 16, v133
	v_and_b32_e32 v133, 0xffff0000, v133
	v_fma_f32 v133, -v10, v133, v85
	v_fma_f32 v85, -v10, v25, v24
	v_lshlrev_b32_e32 v24, 16, v86
	v_and_b32_e32 v86, 0xffff0000, v86
	v_lshlrev_b32_e32 v25, 16, v134
	v_and_b32_e32 v134, 0xffff0000, v134
	v_fma_f32 v134, -v10, v134, v86
	v_fma_f32 v86, -v10, v25, v24
	v_lshlrev_b32_e32 v24, 16, v87
	v_and_b32_e32 v87, 0xffff0000, v87
	v_lshlrev_b32_e32 v25, 16, v135
	v_and_b32_e32 v135, 0xffff0000, v135
	v_fma_f32 v135, -v10, v135, v87
	v_fma_f32 v87, -v10, v25, v24
	v_mul_f32_e32 v16, v132, v132
	v_fmac_f32_e32 v16, v84, v84
	v_mul_f32_e32 v24, v85, v85
	v_mul_f32_e32 v25, v133, v133
	v_add_f32_e32 v16, v24, v16
	v_add_f32_e32 v16, v25, v16
	v_mul_f32_e32 v24, v86, v86
	v_mul_f32_e32 v25, v134, v134
	v_add_f32_e32 v16, v24, v16
	v_add_f32_e32 v16, v25, v16
	v_mul_f32_e32 v24, v87, v87
	v_mul_f32_e32 v25, v135, v135
	v_add_f32_e32 v16, v24, v16
	v_add_f32_e32 v16, v25, v16
	s_waitcnt vmcnt(12)
; __device__ __forceinline__ void attention_phase(char* lds, const bf16_t* Q, const bf16_t* K, const bf16_t* V, bf16_t* O1, bf16_t* O2, bf16_t* OC, const float* lamv, const float* subln, int G, int bid) {
;     ...
;             float a[8], c[8], d[8]; float ss = 0.f;
;             unpack8(*(const u32x4*)(O1 + ro), a); unpack8(*(const u32x4*)(O2 + ro), c);
; #pragma unroll
;             for (int e = 0; e < 8; ++e) { d[e] = a[e] - lam * c[e]; ss += d[e] * d[e]; }
	v_lshlrev_b32_e32 v24, 16, v88
	v_and_b32_e32 v88, 0xffff0000, v88
	v_lshlrev_b32_e32 v25, 16, v136
	v_and_b32_e32 v136, 0xffff0000, v136
	v_fma_f32 v136, -v10, v136, v88
	v_fma_f32 v88, -v10, v25, v24
	v_lshlrev_b32_e32 v24, 16, v89
	v_and_b32_e32 v89, 0xffff0000, v89
	v_lshlrev_b32_e32 v25, 16, v137
	v_and_b32_e32 v137, 0xffff0000, v137
	v_fma_f32 v137, -v10, v137, v89
	v_fma_f32 v89, -v10, v25, v24
	v_lshlrev_b32_e32 v24, 16, v90
	v_and_b32_e32 v90, 0xffff0000, v90
	v_lshlrev_b32_e32 v25, 16, v138
	v_and_b32_e32 v138, 0xffff0000, v138
	v_fma_f32 v138, -v10, v138, v90
	v_fma_f32 v90, -v10, v25, v24
	v_lshlrev_b32_e32 v24, 16, v91
	v_and_b32_e32 v91, 0xffff0000, v91
	v_lshlrev_b32_e32 v25, 16, v139
	v_and_b32_e32 v139, 0xffff0000, v139
	v_fma_f32 v139, -v10, v139, v91
	v_fma_f32 v91, -v10, v25, v24
	v_mul_f32_e32 v17, v136, v136
	v_fmac_f32_e32 v17, v88, v88
	v_mul_f32_e32 v24, v89, v89
	v_mul_f32_e32 v25, v137, v137
	v_add_f32_e32 v17, v24, v17
	v_add_f32_e32 v17, v25, v17
	v_mul_f32_e32 v24, v90, v90
	v_mul_f32_e32 v25, v138, v138
	v_add_f32_e32 v17, v24, v17
	v_add_f32_e32 v17, v25, v17
	v_mul_f32_e32 v24, v91, v91
	v_mul_f32_e32 v25, v139, v139
	v_add_f32_e32 v17, v24, v17
	v_add_f32_e32 v17, v25, v17
	s_waitcnt vmcnt(10)
	v_lshlrev_b32_e32 v24, 16, v92
	v_and_b32_e32 v92, 0xffff0000, v92
	v_lshlrev_b32_e32 v25, 16, v140
	v_and_b32_e32 v140, 0xffff0000, v140
	v_fma_f32 v140, -v10, v140, v92
	v_fma_f32 v92, -v10, v25, v24
	v_lshlrev_b32_e32 v24, 16, v93
	v_and_b32_e32 v93, 0xffff0000, v93
	v_lshlrev_b32_e32 v25, 16, v141
	v_and_b32_e32 v141, 0xffff0000, v141
	v_fma_f32 v141, -v10, v141, v93
	v_fma_f32 v93, -v10, v25, v24
	v_lshlrev_b32_e32 v24, 16, v94
	v_and_b32_e32 v94, 0xffff0000, v94
	v_lshlrev_b32_e32 v25, 16, v142
	v_and_b32_e32 v142, 0xffff0000, v142
	v_fma_f32 v142, -v10, v142, v94
	v_fma_f32 v94, -v10, v25, v24
	v_lshlrev_b32_e32 v24, 16, v95
	v_and_b32_e32 v95, 0xffff0000, v95
	v_lshlrev_b32_e32 v25, 16, v143
	v_and_b32_e32 v143, 0xffff0000, v143
	v_fma_f32 v143, -v10, v143, v95
	v_fma_f32 v95, -v10, v25, v24
	v_mul_f32_e32 v18, v140, v140
	v_fmac_f32_e32 v18, v92, v92
	v_mul_f32_e32 v24, v93, v93
	v_mul_f32_e32 v25, v141, v141
	v_add_f32_e32 v18, v24, v18
	v_add_f32_e32 v18, v25, v18
	v_mul_f32_e32 v24, v94, v94
	v_mul_f32_e32 v25, v142, v142
	v_add_f32_e32 v18, v24, v18
	v_add_f32_e32 v18, v25, v18
	v_mul_f32_e32 v24, v95, v95
	v_mul_f32_e32 v25, v143, v143
	v_add_f32_e32 v18, v24, v18
	v_add_f32_e32 v18, v25, v18
	s_waitcnt vmcnt(8)
	v_lshlrev_b32_e32 v24, 16, v96
	v_and_b32_e32 v96, 0xffff0000, v96
	v_lshlrev_b32_e32 v25, 16, v144
	v_and_b32_e32 v144, 0xffff0000, v144
	v_fma_f32 v144, -v10, v144, v96
	v_fma_f32 v96, -v10, v25, v24
	v_lshlrev_b32_e32 v24, 16, v97
	v_and_b32_e32 v97, 0xffff0000, v97
	v_lshlrev_b32_e32 v25, 16, v145
	v_and_b32_e32 v145, 0xffff0000, v145
	v_fma_f32 v145, -v10, v145, v97
	v_fma_f32 v97, -v10, v25, v24
	v_lshlrev_b32_e32 v24, 16, v98
	v_and_b32_e32 v98, 0xffff0000, v98
	v_lshlrev_b32_e32 v25, 16, v146
	v_and_b32_e32 v146, 0xffff0000, v146
	v_fma_f32 v146, -v10, v146, v98
	v_fma_f32 v98, -v10, v25, v24
	v_lshlrev_b32_e32 v24, 16, v99
	v_and_b32_e32 v99, 0xffff0000, v99
	v_lshlrev_b32_e32 v25, 16, v147
	v_and_b32_e32 v147, 0xffff0000, v147
	v_fma_f32 v147, -v10, v147, v99
	v_fma_f32 v99, -v10, v25, v24
	v_mul_f32_e32 v19, v144, v144
	v_fmac_f32_e32 v19, v96, v96
	v_mul_f32_e32 v24, v97, v97
	v_mul_f32_e32 v25, v145, v145
	v_add_f32_e32 v19, v24, v19
	v_add_f32_e32 v19, v25, v19
	v_mul_f32_e32 v24, v98, v98
	v_mul_f32_e32 v25, v146, v146
	v_add_f32_e32 v19, v24, v19
	v_add_f32_e32 v19, v25, v19
	v_mul_f32_e32 v24, v99, v99
	v_mul_f32_e32 v25, v147, v147
	v_add_f32_e32 v19, v24, v19
	v_add_f32_e32 v19, v25, v19
	s_waitcnt vmcnt(6)
	v_lshlrev_b32_e32 v24, 16, v100
	v_and_b32_e32 v100, 0xffff0000, v100
	v_lshlrev_b32_e32 v25, 16, v148
	v_and_b32_e32 v148, 0xffff0000, v148
	v_fma_f32 v148, -v10, v148, v100
	v_fma_f32 v100, -v10, v25, v24
	v_lshlrev_b32_e32 v24, 16, v101
	v_and_b32_e32 v101, 0xffff0000, v101
	v_lshlrev_b32_e32 v25, 16, v149
	v_and_b32_e32 v149, 0xffff0000, v149
	v_fma_f32 v149, -v10, v149, v101
	v_fma_f32 v101, -v10, v25, v24
	v_lshlrev_b32_e32 v24, 16, v102
	v_and_b32_e32 v102, 0xffff0000, v102
	v_lshlrev_b32_e32 v25, 16, v150
	v_and_b32_e32 v150, 0xffff0000, v150
	v_fma_f32 v150, -v10, v150, v102
	v_fma_f32 v102, -v10, v25, v24
	v_lshlrev_b32_e32 v24, 16, v103
	v_and_b32_e32 v103, 0xffff0000, v103
	v_lshlrev_b32_e32 v25, 16, v151
	v_and_b32_e32 v151, 0xffff0000, v151
	v_fma_f32 v151, -v10, v151, v103
	v_fma_f32 v103, -v10, v25, v24
	v_mul_f32_e32 v20, v148, v148
	v_fmac_f32_e32 v20, v100, v100
	v_mul_f32_e32 v24, v101, v101
	v_mul_f32_e32 v25, v149, v149
	v_add_f32_e32 v20, v24, v20
	v_add_f32_e32 v20, v25, v20
	v_mul_f32_e32 v24, v102, v102
	v_mul_f32_e32 v25, v150, v150
	v_add_f32_e32 v20, v24, v20
	v_add_f32_e32 v20, v25, v20
	v_mul_f32_e32 v24, v103, v103
	v_mul_f32_e32 v25, v151, v151
	v_add_f32_e32 v20, v24, v20
	v_add_f32_e32 v20, v25, v20
	s_waitcnt vmcnt(4)
; __device__ __forceinline__ void attention_phase(char* lds, const bf16_t* Q, const bf16_t* K, const bf16_t* V, bf16_t* O1, bf16_t* O2, bf16_t* OC, const float* lamv, const float* subln, int G, int bid) {
;     ...
;             unpack8(*(const u32x4*)(O1 + ro), a); unpack8(*(const u32x4*)(O2 + ro), c);
; #pragma unroll
;             for (int e = 0; e < 8; ++e) { d[e] = a[e] - lam * c[e]; ss += d[e] * d[e]; }
; #pragma unroll
;             for (int o = 1; o < 32; o <<= 1) ss += __shfl_xor(ss, o);
	v_lshlrev_b32_e32 v24, 16, v104
	v_and_b32_e32 v104, 0xffff0000, v104
	v_lshlrev_b32_e32 v25, 16, v152
	v_and_b32_e32 v152, 0xffff0000, v152
	v_fma_f32 v152, -v10, v152, v104
	v_fma_f32 v104, -v10, v25, v24
	v_lshlrev_b32_e32 v24, 16, v105
	v_and_b32_e32 v105, 0xffff0000, v105
	v_lshlrev_b32_e32 v25, 16, v153
	v_and_b32_e32 v153, 0xffff0000, v153
	v_fma_f32 v153, -v10, v153, v105
	v_fma_f32 v105, -v10, v25, v24
	v_lshlrev_b32_e32 v24, 16, v106
	v_and_b32_e32 v106, 0xffff0000, v106
	v_lshlrev_b32_e32 v25, 16, v154
	v_and_b32_e32 v154, 0xffff0000, v154
	v_fma_f32 v154, -v10, v154, v106
	v_fma_f32 v106, -v10, v25, v24
	v_lshlrev_b32_e32 v24, 16, v107
	v_and_b32_e32 v107, 0xffff0000, v107
	v_lshlrev_b32_e32 v25, 16, v155
	v_and_b32_e32 v155, 0xffff0000, v155
	v_fma_f32 v155, -v10, v155, v107
	v_fma_f32 v107, -v10, v25, v24
	v_mul_f32_e32 v21, v152, v152
	v_fmac_f32_e32 v21, v104, v104
	v_mul_f32_e32 v24, v105, v105
	v_mul_f32_e32 v25, v153, v153
	v_add_f32_e32 v21, v24, v21
	v_add_f32_e32 v21, v25, v21
	v_mul_f32_e32 v24, v106, v106
	v_mul_f32_e32 v25, v154, v154
	v_add_f32_e32 v21, v24, v21
	v_add_f32_e32 v21, v25, v21
	v_mul_f32_e32 v24, v107, v107
	v_mul_f32_e32 v25, v155, v155
	v_add_f32_e32 v21, v24, v21
	v_add_f32_e32 v21, v25, v21
	s_waitcnt vmcnt(2)
	v_lshlrev_b32_e32 v24, 16, v108
	v_and_b32_e32 v108, 0xffff0000, v108
	v_lshlrev_b32_e32 v25, 16, v156
	v_and_b32_e32 v156, 0xffff0000, v156
	v_fma_f32 v156, -v10, v156, v108
	v_fma_f32 v108, -v10, v25, v24
	v_lshlrev_b32_e32 v24, 16, v109
	v_and_b32_e32 v109, 0xffff0000, v109
	v_lshlrev_b32_e32 v25, 16, v157
	v_and_b32_e32 v157, 0xffff0000, v157
	v_fma_f32 v157, -v10, v157, v109
	v_fma_f32 v109, -v10, v25, v24
	v_lshlrev_b32_e32 v24, 16, v110
	v_and_b32_e32 v110, 0xffff0000, v110
	v_lshlrev_b32_e32 v25, 16, v158
	v_and_b32_e32 v158, 0xffff0000, v158
	v_fma_f32 v158, -v10, v158, v110
	v_fma_f32 v110, -v10, v25, v24
	v_lshlrev_b32_e32 v24, 16, v111
	v_and_b32_e32 v111, 0xffff0000, v111
	v_lshlrev_b32_e32 v25, 16, v159
	v_and_b32_e32 v159, 0xffff0000, v159
	v_fma_f32 v159, -v10, v159, v111
	v_fma_f32 v111, -v10, v25, v24
	v_mul_f32_e32 v22, v156, v156
	v_fmac_f32_e32 v22, v108, v108
	v_mul_f32_e32 v24, v109, v109
	v_mul_f32_e32 v25, v157, v157
	v_add_f32_e32 v22, v24, v22
	v_add_f32_e32 v22, v25, v22
	v_mul_f32_e32 v24, v110, v110
	v_mul_f32_e32 v25, v158, v158
	v_add_f32_e32 v22, v24, v22
	v_add_f32_e32 v22, v25, v22
	v_mul_f32_e32 v24, v111, v111
	v_mul_f32_e32 v25, v159, v159
	v_add_f32_e32 v22, v24, v22
	v_add_f32_e32 v22, v25, v22
	s_waitcnt vmcnt(0)
	v_lshlrev_b32_e32 v24, 16, v112
	v_and_b32_e32 v112, 0xffff0000, v112
	v_lshlrev_b32_e32 v25, 16, v160
	v_and_b32_e32 v160, 0xffff0000, v160
	v_fma_f32 v160, -v10, v160, v112
	v_fma_f32 v112, -v10, v25, v24
	v_lshlrev_b32_e32 v24, 16, v113
	v_and_b32_e32 v113, 0xffff0000, v113
	v_lshlrev_b32_e32 v25, 16, v161
	v_and_b32_e32 v161, 0xffff0000, v161
	v_fma_f32 v161, -v10, v161, v113
	v_fma_f32 v113, -v10, v25, v24
	v_lshlrev_b32_e32 v24, 16, v114
	v_and_b32_e32 v114, 0xffff0000, v114
	v_lshlrev_b32_e32 v25, 16, v162
	v_and_b32_e32 v162, 0xffff0000, v162
	v_fma_f32 v162, -v10, v162, v114
	v_fma_f32 v114, -v10, v25, v24
	v_lshlrev_b32_e32 v24, 16, v115
	v_and_b32_e32 v115, 0xffff0000, v115
	v_lshlrev_b32_e32 v25, 16, v163
	v_and_b32_e32 v163, 0xffff0000, v163
	v_fma_f32 v163, -v10, v163, v115
	v_fma_f32 v115, -v10, v25, v24
	v_mul_f32_e32 v23, v160, v160
	v_fmac_f32_e32 v23, v112, v112
	v_mul_f32_e32 v24, v113, v113
	v_mul_f32_e32 v25, v161, v161
	v_add_f32_e32 v23, v24, v23
	v_add_f32_e32 v23, v25, v23
	v_mul_f32_e32 v24, v114, v114
	v_mul_f32_e32 v25, v162, v162
	v_add_f32_e32 v23, v24, v23
	v_add_f32_e32 v23, v25, v23
	v_mul_f32_e32 v24, v115, v115
	v_mul_f32_e32 v25, v163, v163
	v_add_f32_e32 v23, v24, v23
	v_add_f32_e32 v23, v25, v23
	v_add_f32_dpp v16, v16, v16 quad_perm:[1,0,3,2] row_mask:0xf bank_mask:0xf
	v_add_f32_dpp v17, v17, v17 quad_perm:[1,0,3,2] row_mask:0xf bank_mask:0xf
	v_add_f32_dpp v18, v18, v18 quad_perm:[1,0,3,2] row_mask:0xf bank_mask:0xf
	v_add_f32_dpp v19, v19, v19 quad_perm:[1,0,3,2] row_mask:0xf bank_mask:0xf
	v_add_f32_dpp v20, v20, v20 quad_perm:[1,0,3,2] row_mask:0xf bank_mask:0xf
	v_add_f32_dpp v21, v21, v21 quad_perm:[1,0,3,2] row_mask:0xf bank_mask:0xf
	v_add_f32_dpp v22, v22, v22 quad_perm:[1,0,3,2] row_mask:0xf bank_mask:0xf
	v_add_f32_dpp v23, v23, v23 quad_perm:[1,0,3,2] row_mask:0xf bank_mask:0xf
	v_add_f32_dpp v16, v16, v16 quad_perm:[2,3,0,1] row_mask:0xf bank_mask:0xf
	v_add_f32_dpp v17, v17, v17 quad_perm:[2,3,0,1] row_mask:0xf bank_mask:0xf
	v_add_f32_dpp v18, v18, v18 quad_perm:[2,3,0,1] row_mask:0xf bank_mask:0xf
	v_add_f32_dpp v19, v19, v19 quad_perm:[2,3,0,1] row_mask:0xf bank_mask:0xf
	v_add_f32_dpp v20, v20, v20 quad_perm:[2,3,0,1] row_mask:0xf bank_mask:0xf
	v_add_f32_dpp v21, v21, v21 quad_perm:[2,3,0,1] row_mask:0xf bank_mask:0xf
	v_add_f32_dpp v22, v22, v22 quad_perm:[2,3,0,1] row_mask:0xf bank_mask:0xf
	v_add_f32_dpp v23, v23, v23 quad_perm:[2,3,0,1] row_mask:0xf bank_mask:0xf
	v_add_f32_dpp v16, v16, v16 row_half_mirror row_mask:0xf bank_mask:0xf
	v_add_f32_dpp v17, v17, v17 row_half_mirror row_mask:0xf bank_mask:0xf
	v_add_f32_dpp v18, v18, v18 row_half_mirror row_mask:0xf bank_mask:0xf
	v_add_f32_dpp v19, v19, v19 row_half_mirror row_mask:0xf bank_mask:0xf
	v_add_f32_dpp v20, v20, v20 row_half_mirror row_mask:0xf bank_mask:0xf
	v_add_f32_dpp v21, v21, v21 row_half_mirror row_mask:0xf bank_mask:0xf
	v_add_f32_dpp v22, v22, v22 row_half_mirror row_mask:0xf bank_mask:0xf
	v_add_f32_dpp v23, v23, v23 row_half_mirror row_mask:0xf bank_mask:0xf
	v_add_f32_dpp v16, v16, v16 row_mirror row_mask:0xf bank_mask:0xf
	v_add_f32_dpp v17, v17, v17 row_mirror row_mask:0xf bank_mask:0xf
	v_add_f32_dpp v18, v18, v18 row_mirror row_mask:0xf bank_mask:0xf
	v_add_f32_dpp v19, v19, v19 row_mirror row_mask:0xf bank_mask:0xf
	v_add_f32_dpp v20, v20, v20 row_mirror row_mask:0xf bank_mask:0xf
	v_add_f32_dpp v21, v21, v21 row_mirror row_mask:0xf bank_mask:0xf
	v_add_f32_dpp v22, v22, v22 row_mirror row_mask:0xf bank_mask:0xf
	v_add_f32_dpp v23, v23, v23 row_mirror row_mask:0xf bank_mask:0xf
	ds_bpermute_b32 v164, v14, v16
	ds_bpermute_b32 v165, v14, v17
	ds_bpermute_b32 v166, v14, v18
	ds_bpermute_b32 v167, v14, v19
	ds_bpermute_b32 v168, v14, v20
	ds_bpermute_b32 v169, v14, v21
	ds_bpermute_b32 v170, v14, v22
	ds_bpermute_b32 v171, v14, v23
	v_mov_b32_e32 v30, 0x3727c5ac
	s_waitcnt lgkmcnt(7)
; __device__ __forceinline__ u32x4 pack8(const float* f) { u32x4 w; w.x = pk2(f[0], f[1]); w.y = pk2(f[2], f[3]); w.z = pk2(f[4], f[5]); w.w = pk2(f[6], f[7]); return w; }
; __device__ __forceinline__ void attention_phase(char* lds, const bf16_t* Q, const bf16_t* K, const bf16_t* V, bf16_t* O1, bf16_t* O2, bf16_t* OC, const float* lamv, const float* subln, int G, int bid) {
;     ...
; #pragma unroll
;             for (int o = 1; o < 32; o <<= 1) ss += __shfl_xor(ss, o);
;             const float r = rsqrtf(ss * (1.f / 256.f) + 1e-5f) * 0.8f;
; #pragma unroll
;             for (int e = 0; e < 8; ++e) d[e] = d[e] * r * g[e];
;             *(u32x4*)(OC + ro) = pack8(d);
	v_add_f32_e32 v16, v16, v164
	s_waitcnt lgkmcnt(6)
	v_add_f32_e32 v17, v17, v165
	s_waitcnt lgkmcnt(5)
	v_add_f32_e32 v18, v18, v166
	s_waitcnt lgkmcnt(4)
	v_add_f32_e32 v19, v19, v167
	s_waitcnt lgkmcnt(3)
	v_add_f32_e32 v20, v20, v168
	s_waitcnt lgkmcnt(2)
	v_add_f32_e32 v21, v21, v169
	s_waitcnt lgkmcnt(1)
	v_add_f32_e32 v22, v22, v170
	s_waitcnt lgkmcnt(0)
	v_add_f32_e32 v23, v23, v171
	v_fmamk_f32 v16, v16, 0x3b800000, v30
	v_cmp_gt_f32_e32 vcc, s15, v16
	v_mul_f32_e32 v24, 0x4b800000, v16
	s_nop 0
	v_cndmask_b32_e32 v16, v16, v24, vcc
	v_rsq_f32_e32 v16, v16
	s_nop 0
	v_mul_f32_e32 v24, 0x45800000, v16
	v_cndmask_b32_e32 v16, v16, v24, vcc
	v_mul_f32_e32 v16, 0x3f4ccccd, v16
	v_mul_f32_e32 v84, v84, v16
	v_mul_f32_e32 v132, v132, v16
	v_mul_f32_e32 v84, v0, v84
	v_mul_f32_e32 v132, v1, v132
	v_mul_f32_e32 v85, v85, v16
	v_mul_f32_e32 v133, v133, v16
	v_mul_f32_e32 v85, v2, v85
	v_mul_f32_e32 v133, v3, v133
	v_mul_f32_e32 v86, v86, v16
	v_mul_f32_e32 v134, v134, v16
	v_mul_f32_e32 v86, v4, v86
	v_mul_f32_e32 v134, v5, v134
	v_mul_f32_e32 v87, v87, v16
	v_mul_f32_e32 v135, v135, v16
	v_mul_f32_e32 v87, v6, v87
	v_mul_f32_e32 v135, v7, v135
	v_cvt_pk_bf16_f32 v84, v84, v132
	v_cvt_pk_bf16_f32 v85, v85, v133
	v_cvt_pk_bf16_f32 v86, v86, v134
	v_cvt_pk_bf16_f32 v87, v87, v135
	v_lshl_add_u64 v[26:27], s[58:59], 0, v[32:33]
	global_store_dwordx4 v[26:27], v[84:87], off
	v_fmamk_f32 v17, v17, 0x3b800000, v30
	v_cmp_gt_f32_e32 vcc, s15, v17
	v_mul_f32_e32 v24, 0x4b800000, v17
	s_nop 0
	v_cndmask_b32_e32 v17, v17, v24, vcc
	v_rsq_f32_e32 v17, v17
	s_nop 0
	v_mul_f32_e32 v24, 0x45800000, v17
	v_cndmask_b32_e32 v17, v17, v24, vcc
	v_mul_f32_e32 v17, 0x3f4ccccd, v17
	v_mul_f32_e32 v88, v88, v17
	v_mul_f32_e32 v136, v136, v17
	v_mul_f32_e32 v88, v0, v88
	v_mul_f32_e32 v136, v1, v136
	v_mul_f32_e32 v89, v89, v17
	v_mul_f32_e32 v137, v137, v17
	v_mul_f32_e32 v89, v2, v89
	v_mul_f32_e32 v137, v3, v137
	v_mul_f32_e32 v90, v90, v17
	v_mul_f32_e32 v138, v138, v17
	v_mul_f32_e32 v90, v4, v90
	v_mul_f32_e32 v138, v5, v138
	v_mul_f32_e32 v91, v91, v17
	v_mul_f32_e32 v139, v139, v17
	v_mul_f32_e32 v91, v6, v91
	v_mul_f32_e32 v139, v7, v139
	v_cvt_pk_bf16_f32 v88, v88, v136
	v_cvt_pk_bf16_f32 v89, v89, v137
	v_cvt_pk_bf16_f32 v90, v90, v138
	v_cvt_pk_bf16_f32 v91, v91, v139
	v_lshl_add_u64 v[26:27], s[58:59], 0, v[34:35]
	global_store_dwordx4 v[26:27], v[88:91], off
	v_fmamk_f32 v18, v18, 0x3b800000, v30
	v_cmp_gt_f32_e32 vcc, s15, v18
	v_mul_f32_e32 v24, 0x4b800000, v18
	s_nop 0
	v_cndmask_b32_e32 v18, v18, v24, vcc
	v_rsq_f32_e32 v18, v18
	s_nop 0
	v_mul_f32_e32 v24, 0x45800000, v18
	v_cndmask_b32_e32 v18, v18, v24, vcc
	v_mul_f32_e32 v18, 0x3f4ccccd, v18
	v_mul_f32_e32 v92, v92, v18
	v_mul_f32_e32 v140, v140, v18
	v_mul_f32_e32 v92, v0, v92
	v_mul_f32_e32 v140, v1, v140
	v_mul_f32_e32 v93, v93, v18
	v_mul_f32_e32 v141, v141, v18
	v_mul_f32_e32 v93, v2, v93
	v_mul_f32_e32 v141, v3, v141
	v_mul_f32_e32 v94, v94, v18
	v_mul_f32_e32 v142, v142, v18
	v_mul_f32_e32 v94, v4, v94
	v_mul_f32_e32 v142, v5, v142
	v_mul_f32_e32 v95, v95, v18
	v_mul_f32_e32 v143, v143, v18
	v_mul_f32_e32 v95, v6, v95
	v_mul_f32_e32 v143, v7, v143
	v_cvt_pk_bf16_f32 v92, v92, v140
	v_cvt_pk_bf16_f32 v93, v93, v141
	v_cvt_pk_bf16_f32 v94, v94, v142
	v_cvt_pk_bf16_f32 v95, v95, v143
	v_lshl_add_u64 v[26:27], s[58:59], 0, v[36:37]
	global_store_dwordx4 v[26:27], v[92:95], off
	v_fmamk_f32 v19, v19, 0x3b800000, v30
	v_cmp_gt_f32_e32 vcc, s15, v19
	v_mul_f32_e32 v24, 0x4b800000, v19
	s_nop 0
	v_cndmask_b32_e32 v19, v19, v24, vcc
	v_rsq_f32_e32 v19, v19
	s_nop 0
	v_mul_f32_e32 v24, 0x45800000, v19
	v_cndmask_b32_e32 v19, v19, v24, vcc
	v_mul_f32_e32 v19, 0x3f4ccccd, v19
	v_mul_f32_e32 v96, v96, v19
	v_mul_f32_e32 v144, v144, v19
	v_mul_f32_e32 v96, v0, v96
	v_mul_f32_e32 v144, v1, v144
	v_mul_f32_e32 v97, v97, v19
	v_mul_f32_e32 v145, v145, v19
	v_mul_f32_e32 v97, v2, v97
	v_mul_f32_e32 v145, v3, v145
	v_mul_f32_e32 v98, v98, v19
	v_mul_f32_e32 v146, v146, v19
	v_mul_f32_e32 v98, v4, v98
	v_mul_f32_e32 v146, v5, v146
	v_mul_f32_e32 v99, v99, v19
	v_mul_f32_e32 v147, v147, v19
	v_mul_f32_e32 v99, v6, v99
	v_mul_f32_e32 v147, v7, v147
	v_cvt_pk_bf16_f32 v96, v96, v144
	v_cvt_pk_bf16_f32 v97, v97, v145
	v_cvt_pk_bf16_f32 v98, v98, v146
	v_cvt_pk_bf16_f32 v99, v99, v147
	v_lshl_add_u64 v[26:27], s[58:59], 0, v[38:39]
	global_store_dwordx4 v[26:27], v[96:99], off
	v_fmamk_f32 v20, v20, 0x3b800000, v30
	v_cmp_gt_f32_e32 vcc, s15, v20
; __device__ __forceinline__ u32x4 pack8(const float* f) { u32x4 w; w.x = pk2(f[0], f[1]); w.y = pk2(f[2], f[3]); w.z = pk2(f[4], f[5]); w.w = pk2(f[6], f[7]); return w; }
; __device__ __forceinline__ void attention_phase(char* lds, const bf16_t* Q, const bf16_t* K, const bf16_t* V, bf16_t* O1, bf16_t* O2, bf16_t* OC, const float* lamv, const float* subln, int G, int bid) {
;     ...
;     for (int L = bid; L < total; L += G) {
;     ...
;             const float r = rsqrtf(ss * (1.f / 256.f) + 1e-5f) * 0.8f;
; #pragma unroll
;             for (int e = 0; e < 8; ++e) d[e] = d[e] * r * g[e];
;             *(u32x4*)(OC + ro) = pack8(d);
;         }
;         __syncthreads();
	v_mul_f32_e32 v24, 0x4b800000, v20
	s_nop 0
	v_cndmask_b32_e32 v20, v20, v24, vcc
	v_rsq_f32_e32 v20, v20
	s_nop 0
	v_mul_f32_e32 v24, 0x45800000, v20
	v_cndmask_b32_e32 v20, v20, v24, vcc
	v_mul_f32_e32 v20, 0x3f4ccccd, v20
	v_mul_f32_e32 v100, v100, v20
	v_mul_f32_e32 v148, v148, v20
	v_mul_f32_e32 v100, v0, v100
	v_mul_f32_e32 v148, v1, v148
	v_mul_f32_e32 v101, v101, v20
	v_mul_f32_e32 v149, v149, v20
	v_mul_f32_e32 v101, v2, v101
	v_mul_f32_e32 v149, v3, v149
	v_mul_f32_e32 v102, v102, v20
	v_mul_f32_e32 v150, v150, v20
	v_mul_f32_e32 v102, v4, v102
	v_mul_f32_e32 v150, v5, v150
	v_mul_f32_e32 v103, v103, v20
	v_mul_f32_e32 v151, v151, v20
	v_mul_f32_e32 v103, v6, v103
	v_mul_f32_e32 v151, v7, v151
	v_cvt_pk_bf16_f32 v100, v100, v148
	v_cvt_pk_bf16_f32 v101, v101, v149
	v_cvt_pk_bf16_f32 v102, v102, v150
	v_cvt_pk_bf16_f32 v103, v103, v151
	v_lshl_add_u64 v[26:27], s[58:59], 0, v[40:41]
	global_store_dwordx4 v[26:27], v[100:103], off
	v_fmamk_f32 v21, v21, 0x3b800000, v30
	v_cmp_gt_f32_e32 vcc, s15, v21
	v_mul_f32_e32 v24, 0x4b800000, v21
	s_nop 0
	v_cndmask_b32_e32 v21, v21, v24, vcc
	v_rsq_f32_e32 v21, v21
	s_nop 0
	v_mul_f32_e32 v24, 0x45800000, v21
	v_cndmask_b32_e32 v21, v21, v24, vcc
	v_mul_f32_e32 v21, 0x3f4ccccd, v21
	v_mul_f32_e32 v104, v104, v21
	v_mul_f32_e32 v152, v152, v21
	v_mul_f32_e32 v104, v0, v104
	v_mul_f32_e32 v152, v1, v152
	v_mul_f32_e32 v105, v105, v21
	v_mul_f32_e32 v153, v153, v21
	v_mul_f32_e32 v105, v2, v105
	v_mul_f32_e32 v153, v3, v153
	v_mul_f32_e32 v106, v106, v21
	v_mul_f32_e32 v154, v154, v21
	v_mul_f32_e32 v106, v4, v106
	v_mul_f32_e32 v154, v5, v154
	v_mul_f32_e32 v107, v107, v21
	v_mul_f32_e32 v155, v155, v21
	v_mul_f32_e32 v107, v6, v107
	v_mul_f32_e32 v155, v7, v155
	v_cvt_pk_bf16_f32 v104, v104, v152
	v_cvt_pk_bf16_f32 v105, v105, v153
	v_cvt_pk_bf16_f32 v106, v106, v154
	v_cvt_pk_bf16_f32 v107, v107, v155
	v_lshl_add_u64 v[26:27], s[58:59], 0, v[42:43]
	global_store_dwordx4 v[26:27], v[104:107], off
	v_fmamk_f32 v22, v22, 0x3b800000, v30
	v_cmp_gt_f32_e32 vcc, s15, v22
	v_mul_f32_e32 v24, 0x4b800000, v22
	s_nop 0
	v_cndmask_b32_e32 v22, v22, v24, vcc
	v_rsq_f32_e32 v22, v22
	s_nop 0
	v_mul_f32_e32 v24, 0x45800000, v22
	v_cndmask_b32_e32 v22, v22, v24, vcc
	v_mul_f32_e32 v22, 0x3f4ccccd, v22
	v_mul_f32_e32 v108, v108, v22
	v_mul_f32_e32 v156, v156, v22
	v_mul_f32_e32 v108, v0, v108
	v_mul_f32_e32 v156, v1, v156
	v_mul_f32_e32 v109, v109, v22
	v_mul_f32_e32 v157, v157, v22
	v_mul_f32_e32 v109, v2, v109
	v_mul_f32_e32 v157, v3, v157
	v_mul_f32_e32 v110, v110, v22
	v_mul_f32_e32 v158, v158, v22
	v_mul_f32_e32 v110, v4, v110
	v_mul_f32_e32 v158, v5, v158
	v_mul_f32_e32 v111, v111, v22
	v_mul_f32_e32 v159, v159, v22
	v_mul_f32_e32 v111, v6, v111
	v_mul_f32_e32 v159, v7, v159
	v_cvt_pk_bf16_f32 v108, v108, v156
	v_cvt_pk_bf16_f32 v109, v109, v157
	v_cvt_pk_bf16_f32 v110, v110, v158
	v_cvt_pk_bf16_f32 v111, v111, v159
	v_lshl_add_u64 v[26:27], s[58:59], 0, v[44:45]
	global_store_dwordx4 v[26:27], v[108:111], off
	v_fmamk_f32 v23, v23, 0x3b800000, v30
	v_cmp_gt_f32_e32 vcc, s15, v23
	v_mul_f32_e32 v24, 0x4b800000, v23
	s_nop 0
	v_cndmask_b32_e32 v23, v23, v24, vcc
	v_rsq_f32_e32 v23, v23
	s_nop 0
	v_mul_f32_e32 v24, 0x45800000, v23
	v_cndmask_b32_e32 v23, v23, v24, vcc
	v_mul_f32_e32 v23, 0x3f4ccccd, v23
	v_mul_f32_e32 v112, v112, v23
	v_mul_f32_e32 v160, v160, v23
	v_mul_f32_e32 v112, v0, v112
	v_mul_f32_e32 v160, v1, v160
	v_mul_f32_e32 v113, v113, v23
	v_mul_f32_e32 v161, v161, v23
	v_mul_f32_e32 v113, v2, v113
	v_mul_f32_e32 v161, v3, v161
	v_mul_f32_e32 v114, v114, v23
	v_mul_f32_e32 v162, v162, v23
	v_mul_f32_e32 v114, v4, v114
	v_mul_f32_e32 v162, v5, v162
	v_mul_f32_e32 v115, v115, v23
	v_mul_f32_e32 v163, v163, v23
	v_mul_f32_e32 v115, v6, v115
	v_mul_f32_e32 v163, v7, v163
	v_cvt_pk_bf16_f32 v112, v112, v160
	v_cvt_pk_bf16_f32 v113, v113, v161
	v_cvt_pk_bf16_f32 v114, v114, v162
	v_cvt_pk_bf16_f32 v115, v115, v163
	v_lshl_add_u64 v[26:27], s[58:59], 0, v[46:47]
	global_store_dwordx4 v[26:27], v[112:115], off
	s_add_i32 s2, s2, 16
	s_cmp_eq_u32 s2, 64
	s_cbranch_scc0 .Lcmb_loop
	s_add_i32 s10, s10, s78
	s_cmpk_gt_i32 s10, 0xff
	s_barrier
	s_cbranch_scc0 .LBB0_497
	v_readlane_b32 s88, v254, 63
	v_readlane_b32 s86, v255, 1
	v_readlane_b32 s89, v255, 0
	s_movk_i32 s68, 0x4000
	s_mov_b32 s69, 0x10000
	s_mov_b32 s37, 0x14000
	s_mov_b32 s40, 0x18000
	s_mov_b32 s41, 0x8000
	s_mov_b64 s[26:27], 0x1000
	s_mov_b64 s[74:75], 0x1800
